# scanchoist on v111: prompt scan step (c) issues its eight chunk end-state LDS reads up front, the chain waits lgkmcnt 7..0
# speedup vs baseline: 1.0007x; 1.0007x over previous
.LBB0_1006:
	s_lshr_b32 s31, s35, 6
	s_and_b32 s38, s8, 1
	s_lshl_b32 s2, s31, 3
	s_or_b32 s39, s2, 1
	s_mul_i32 s2, s38, 0x8400
	v_add_u32_e32 v226, s2, v208
	v_add_u32_e32 v227, v226, v210
	s_and_b32 s34, s35, 0xffffffc0
	v_add3_u32 v90, v209, s34, v210
	s_mul_i32 s2, s31, 0x1080
	s_cmp_eq_u32 s8, 0
	ds_read_b128 v[92:95], v227
	ds_read_b128 v[96:99], v227 offset:64
	ds_read_b128 v[100:103], v227 offset:128
	ds_read_b128 v[104:107], v227 offset:192
	ds_read_b128 v[108:111], v227 offset:256
	ds_read_b128 v[112:115], v227 offset:320
	ds_read_b128 v[116:119], v227 offset:384
	ds_read_b128 v[120:123], v227 offset:448
	s_waitcnt lgkmcnt(7)
	v_mfma_f32_16x16x32_bf16 v[124:127], v[2:5], v[92:95], 0
	ds_read_b128 v[92:95], v227 offset:8448
	s_waitcnt lgkmcnt(7)
	v_mfma_f32_16x16x32_bf16 v[124:127], v[6:9], v[96:99], v[124:127]
	ds_read_b128 v[96:99], v227 offset:8512
	s_waitcnt lgkmcnt(7)
	v_mfma_f32_16x16x32_bf16 v[124:127], v[10:13], v[100:103], v[124:127]
	ds_read_b128 v[100:103], v227 offset:8576
	s_waitcnt lgkmcnt(7)
	v_mfma_f32_16x16x32_bf16 v[124:127], v[14:17], v[104:107], v[124:127]
	ds_read_b128 v[104:107], v227 offset:8640
	s_waitcnt lgkmcnt(7)
	v_mfma_f32_16x16x32_bf16 v[124:127], v[18:21], v[108:111], v[124:127]
	ds_read_b128 v[108:111], v227 offset:8704
	s_waitcnt vmcnt(9) lgkmcnt(7)
	v_mfma_f32_16x16x32_bf16 v[124:127], v[26:29], v[112:115], v[124:127]
	ds_read_b128 v[112:115], v227 offset:8768
	s_waitcnt vmcnt(8) lgkmcnt(7)
	v_mfma_f32_16x16x32_bf16 v[124:127], v[30:33], v[116:119], v[124:127]
	ds_read_b128 v[116:119], v227 offset:8832
	s_waitcnt vmcnt(7) lgkmcnt(7)
	v_mfma_f32_16x16x32_bf16 v[124:127], v[34:37], v[120:123], v[124:127]
	ds_read_b128 v[120:123], v227 offset:8896
	s_waitcnt lgkmcnt(7)
	v_mfma_f32_16x16x32_bf16 v[128:131], v[2:5], v[92:95], 0
	ds_read_b128 v[92:95], v227 offset:16896
	s_waitcnt lgkmcnt(7)
	v_mfma_f32_16x16x32_bf16 v[128:131], v[6:9], v[96:99], v[128:131]
	ds_read_b128 v[96:99], v227 offset:16960
	s_waitcnt lgkmcnt(7)
	v_mfma_f32_16x16x32_bf16 v[128:131], v[10:13], v[100:103], v[128:131]
	ds_read_b128 v[100:103], v227 offset:17024
	s_waitcnt lgkmcnt(7)
	v_mfma_f32_16x16x32_bf16 v[128:131], v[14:17], v[104:107], v[128:131]
	ds_read_b128 v[104:107], v227 offset:17088
	s_waitcnt lgkmcnt(7)
	v_mfma_f32_16x16x32_bf16 v[128:131], v[18:21], v[108:111], v[128:131]
	ds_read_b128 v[108:111], v227 offset:17152
	s_waitcnt lgkmcnt(7)
	v_mfma_f32_16x16x32_bf16 v[128:131], v[26:29], v[112:115], v[128:131]
	ds_read_b128 v[112:115], v227 offset:17216
	s_waitcnt lgkmcnt(7)
	v_mfma_f32_16x16x32_bf16 v[128:131], v[30:33], v[116:119], v[128:131]
	ds_read_b128 v[116:119], v227 offset:17280
	s_waitcnt lgkmcnt(7)
	v_mfma_f32_16x16x32_bf16 v[128:131], v[34:37], v[120:123], v[128:131]
	ds_read_b128 v[120:123], v227 offset:17344
	s_waitcnt lgkmcnt(7)
	v_mfma_f32_16x16x32_bf16 v[132:135], v[2:5], v[92:95], 0
	ds_read_b128 v[92:95], v227 offset:25344
	s_waitcnt lgkmcnt(7)
	v_mfma_f32_16x16x32_bf16 v[132:135], v[6:9], v[96:99], v[132:135]
	ds_read_b128 v[96:99], v227 offset:25408
	s_waitcnt lgkmcnt(7)
	v_mfma_f32_16x16x32_bf16 v[132:135], v[10:13], v[100:103], v[132:135]
	ds_read_b128 v[100:103], v227 offset:25472
	s_waitcnt lgkmcnt(7)
	v_mfma_f32_16x16x32_bf16 v[132:135], v[14:17], v[104:107], v[132:135]
	ds_read_b128 v[104:107], v227 offset:25536
	s_waitcnt lgkmcnt(7)
	v_mfma_f32_16x16x32_bf16 v[132:135], v[18:21], v[108:111], v[132:135]
	ds_read_b128 v[108:111], v227 offset:25600
	s_waitcnt lgkmcnt(7)
	v_mfma_f32_16x16x32_bf16 v[132:135], v[26:29], v[112:115], v[132:135]
	ds_read_b128 v[112:115], v227 offset:25664
	s_waitcnt lgkmcnt(7)
	v_mfma_f32_16x16x32_bf16 v[132:135], v[30:33], v[116:119], v[132:135]
	ds_read_b128 v[116:119], v227 offset:25728
	s_waitcnt lgkmcnt(7)
	v_mfma_f32_16x16x32_bf16 v[132:135], v[34:37], v[120:123], v[132:135]
	ds_read_b128 v[120:123], v227 offset:25792
	s_waitcnt lgkmcnt(7)
	v_mfma_f32_16x16x32_bf16 v[136:139], v[2:5], v[92:95], 0
	s_waitcnt lgkmcnt(6)
	v_mfma_f32_16x16x32_bf16 v[136:139], v[6:9], v[96:99], v[136:139]
	s_waitcnt lgkmcnt(5)
	v_mfma_f32_16x16x32_bf16 v[136:139], v[10:13], v[100:103], v[136:139]
	s_waitcnt lgkmcnt(4)
	v_mfma_f32_16x16x32_bf16 v[136:139], v[14:17], v[104:107], v[136:139]
	s_waitcnt lgkmcnt(3)
	v_mfma_f32_16x16x32_bf16 v[136:139], v[18:21], v[108:111], v[136:139]
	s_waitcnt lgkmcnt(2)
	v_mfma_f32_16x16x32_bf16 v[136:139], v[26:29], v[112:115], v[136:139]
	s_waitcnt lgkmcnt(1)
	v_mfma_f32_16x16x32_bf16 v[136:139], v[30:33], v[116:119], v[136:139]
	s_waitcnt lgkmcnt(0)
	v_mfma_f32_16x16x32_bf16 v[136:139], v[34:37], v[120:123], v[136:139]
	s_nop 7
	ds_write_b128 v90, v[124:127]
	ds_write_b128 v90, v[128:131] offset:8448
	ds_write_b128 v90, v[132:135] offset:16896
	ds_write_b128 v90, v[136:139] offset:25344
	s_waitcnt lgkmcnt(0)
	s_barrier
	v_add_u32_e32 v82, s2, v216
	ds_read2st64_b32 v[82:83], v82 offset1:1
	s_mul_i32 s2, s39, 0x210
	v_add_u32_e32 v90, s2, v216
	ds_read2st64_b32 v[84:85], v90 offset1:1
	ds_read2_b32 v[86:87], v90 offset0:132 offset1:196
	v_add_u32_e32 v88, 32, v90
	ds_read2st64_b32 v[88:89], v88 offset0:4 offset1:5
	v_add_u32_e32 v91, 48, v90
	ds_read2st64_b32 v[98:99], v91 offset0:6 offset1:7
	v_add_u32_e32 v91, 64, v90
	ds_read2st64_b32 v[100:101], v91 offset0:8 offset1:9
	v_add_u32_e32 v91, 0x50, v90
	v_add_u32_e32 v90, 0x60, v90
	ds_read2st64_b32 v[102:103], v91 offset0:10 offset1:11
	ds_read2st64_b32 v[104:105], v90 offset0:12 offset1:13
	s_waitcnt lgkmcnt(7)
	v_mov_b32_e32 v96, v83
	v_mov_b32_e32 v97, v82
	v_pk_fma_f32 v[82:83], v[190:191], 0, v[96:97] op_sel_hi:[1,0,1]
	s_nop 0
	v_pk_fma_f32 v[82:83], v[188:189], 0, v[82:83] op_sel_hi:[1,0,1]
	s_waitcnt lgkmcnt(6)
	v_mov_b32_e32 v94, v85
	v_mov_b32_e32 v95, v84
	v_pk_fma_f32 v[84:85], v[190:191], v[82:83], v[94:95] op_sel:[0,1,0] op_sel_hi:[1,0,1]
	s_nop 0
	v_pk_fma_f32 v[82:83], v[188:189], v[82:83], v[84:85]
	s_waitcnt lgkmcnt(5)
	v_mov_b32_e32 v92, v87
	v_mov_b32_e32 v93, v86
	v_pk_fma_f32 v[84:85], v[190:191], v[82:83], v[92:93] op_sel:[0,1,0] op_sel_hi:[1,0,1]
	s_nop 0
	v_pk_fma_f32 v[82:83], v[188:189], v[82:83], v[84:85]
	s_waitcnt lgkmcnt(4)
	v_mov_b32_e32 v90, v89
	v_mov_b32_e32 v91, v88
	v_pk_fma_f32 v[84:85], v[190:191], v[82:83], v[90:91] op_sel:[0,1,0] op_sel_hi:[1,0,1]
	s_waitcnt lgkmcnt(3)
	v_mov_b32_e32 v88, v99
	v_pk_fma_f32 v[82:83], v[188:189], v[82:83], v[84:85]
	v_mov_b32_e32 v89, v98
	v_pk_fma_f32 v[84:85], v[190:191], v[82:83], v[88:89] op_sel:[0,1,0] op_sel_hi:[1,0,1]
	s_waitcnt lgkmcnt(2)
	v_mov_b32_e32 v86, v101
	v_pk_fma_f32 v[82:83], v[188:189], v[82:83], v[84:85]
	v_mov_b32_e32 v87, v100
	v_pk_fma_f32 v[84:85], v[190:191], v[82:83], v[86:87] op_sel:[0,1,0] op_sel_hi:[1,0,1]
	s_nop 0
	v_pk_fma_f32 v[82:83], v[188:189], v[82:83], v[84:85]
	s_waitcnt lgkmcnt(1)
	v_mov_b32_e32 v84, v103
	v_mov_b32_e32 v85, v102
	v_pk_fma_f32 v[98:99], v[190:191], v[82:83], v[84:85] op_sel:[0,1,0] op_sel_hi:[1,0,1]
	s_nop 0
	v_pk_fma_f32 v[98:99], v[188:189], v[82:83], v[98:99]
	s_waitcnt lgkmcnt(0)
	v_mov_b32_e32 v82, v105
	v_mov_b32_e32 v83, v104
	v_pk_fma_f32 v[100:101], v[190:191], v[98:99], v[82:83] op_sel:[0,1,0] op_sel_hi:[1,0,1]
	s_nop 0
	v_pk_fma_f32 v[98:99], v[188:189], v[98:99], v[100:101]
	v_lshl_add_u32 v100, s34, 3, v211
	v_pk_mov_b32 v[98:99], v[98:99], v[98:99] op_sel:[1,0]
	ds_write_b64 v100, v[98:99]
	s_waitcnt lgkmcnt(0)
	s_barrier
	s_cbranch_scc1 .LBB0_1019
	v_lshl_add_u32 v98, s38, 9, v212
	ds_read_b64 v[98:99], v98
	s_cmp_lt_u32 s35, 64
	v_mov_b32_e32 v100, v218
	s_mov_b32 s2, s31
	s_cbranch_scc1 .LBB0_1009
